# S5 prompt block loop hand-rewritten: scalar v_fmac scan in place, no movs
# speedup vs baseline: 1.0166x; 1.0166x over previous
.LBB0_359:
	s_or_b64 exec, exec, s[26:27]
	v_lshl_add_u64 v[4:5], v[94:95], 0, s[24:25]
	s_and_b64 vcc, exec, s[6:7]
	v_xor_b32_e32 v74, 0x80000000, v78
	s_cbranch_vccnz .Ls5p_mfma
	global_load_dwordx2 v[100:101], v[4:5], off
.Ls5p_mfma:
	v_mfma_f32_16x16x32_bf16 v[66:69], v[62:65], v[10:13], 0
	v_mfma_f32_16x16x32_bf16 v[70:73], v[62:65], v[6:9], 0
	v_mfma_f32_16x16x32_bf16 v[102:105], v[62:65], v[18:21], 0
	v_mfma_f32_16x16x32_bf16 v[106:109], v[62:65], v[14:17], 0
	v_mfma_f32_16x16x32_bf16 v[110:113], v[62:65], v[26:29], 0
	v_mfma_f32_16x16x32_bf16 v[114:117], v[62:65], v[22:25], 0
	v_mfma_f32_16x16x32_bf16 v[132:135], v[62:65], v[34:37], 0
	v_mfma_f32_16x16x32_bf16 v[136:139], v[62:65], v[30:33], 0
	s_nop 0
	ds_write_b128 v128, v[66:69]
	ds_write_b128 v128, v[70:73] offset:1280
	ds_write_b128 v128, v[102:105] offset:2560
	ds_write_b128 v128, v[106:109] offset:3840
	ds_write_b128 v128, v[110:113] offset:5120
	ds_write_b128 v128, v[114:117] offset:6400
	ds_write_b128 v128, v[132:135] offset:7680
	ds_write_b128 v128, v[136:139] offset:8960
	s_waitcnt lgkmcnt(0)
	ds_read_b128 v[66:69], v130
	ds_read_b128 v[110:113], v130 offset:5120
	ds_read_b128 v[70:73], v130 offset:16
	ds_read_b128 v[114:117], v130 offset:5136
	ds_read_b128 v[102:105], v130 offset:32
	ds_read_b128 v[132:135], v130 offset:5152
	ds_read_b128 v[106:109], v130 offset:48
	ds_read_b128 v[136:139], v130 offset:5168
	s_cbranch_vccnz .Ls5p_scan0
	s_waitcnt lgkmcnt(6)
	v_fmac_f32_e32 v66, v80, v99
	v_fmac_f32_e32 v110, v80, v98
	v_fmac_f32_e32 v66, v74, v98
	v_fmac_f32_e32 v110, v78, v99
	v_fmac_f32_e32 v67, v80, v66
	v_fmac_f32_e32 v111, v80, v110
	v_fmac_f32_e32 v67, v74, v110
	v_fmac_f32_e32 v111, v78, v66
	v_fmac_f32_e32 v68, v80, v67
	v_fmac_f32_e32 v112, v80, v111
	v_fmac_f32_e32 v68, v74, v111
	v_fmac_f32_e32 v112, v78, v67
	v_fmac_f32_e32 v69, v80, v68
	v_fmac_f32_e32 v113, v80, v112
	v_fmac_f32_e32 v69, v74, v112
	v_fmac_f32_e32 v113, v78, v68
	ds_write_b128 v130, v[66:69]
	ds_write_b128 v130, v[110:113] offset:5120
	s_waitcnt lgkmcnt(6)
	v_fmac_f32_e32 v70, v80, v69
	v_fmac_f32_e32 v114, v80, v113
	v_fmac_f32_e32 v70, v74, v113
	v_fmac_f32_e32 v114, v78, v69
	v_fmac_f32_e32 v71, v80, v70
	v_fmac_f32_e32 v115, v80, v114
	v_fmac_f32_e32 v71, v74, v114
	v_fmac_f32_e32 v115, v78, v70
	v_fmac_f32_e32 v72, v80, v71
	v_fmac_f32_e32 v116, v80, v115
	v_fmac_f32_e32 v72, v74, v115
	v_fmac_f32_e32 v116, v78, v71
	v_fmac_f32_e32 v73, v80, v72
	v_fmac_f32_e32 v117, v80, v116
	v_fmac_f32_e32 v73, v74, v116
	v_fmac_f32_e32 v117, v78, v72
	ds_write_b128 v130, v[70:73] offset:16
	ds_write_b128 v130, v[114:117] offset:5136
	s_waitcnt lgkmcnt(6)
	v_fmac_f32_e32 v102, v80, v73
	v_fmac_f32_e32 v132, v80, v117
	v_fmac_f32_e32 v102, v74, v117
	v_fmac_f32_e32 v132, v78, v73
	v_fmac_f32_e32 v103, v80, v102
	v_fmac_f32_e32 v133, v80, v132
	v_fmac_f32_e32 v103, v74, v132
	v_fmac_f32_e32 v133, v78, v102
	v_fmac_f32_e32 v104, v80, v103
	v_fmac_f32_e32 v134, v80, v133
	v_fmac_f32_e32 v104, v74, v133
	v_fmac_f32_e32 v134, v78, v103
	v_fmac_f32_e32 v105, v80, v104
	v_fmac_f32_e32 v135, v80, v134
	v_fmac_f32_e32 v105, v74, v134
	v_fmac_f32_e32 v135, v78, v104
	ds_write_b128 v130, v[102:105] offset:32
	ds_write_b128 v130, v[132:135] offset:5152
	s_waitcnt lgkmcnt(6)
	v_fmac_f32_e32 v106, v80, v105
	v_fmac_f32_e32 v136, v80, v135
	v_fmac_f32_e32 v106, v74, v135
	v_fmac_f32_e32 v136, v78, v105
	v_fmac_f32_e32 v107, v80, v106
	v_fmac_f32_e32 v137, v80, v136
	v_fmac_f32_e32 v107, v74, v136
	v_fmac_f32_e32 v137, v78, v106
	v_fmac_f32_e32 v108, v80, v107
	v_fmac_f32_e32 v138, v80, v137
	v_fmac_f32_e32 v108, v74, v137
	v_fmac_f32_e32 v138, v78, v107
	v_fmac_f32_e32 v109, v80, v108
	v_fmac_f32_e32 v139, v80, v138
	v_fmac_f32_e32 v109, v74, v138
	v_fmac_f32_e32 v139, v78, v108
	v_mov_b32_e32 v99, v109
	v_mov_b32_e32 v98, v139
	ds_write_b128 v130, v[106:109] offset:48
	ds_write_b128 v130, v[136:139] offset:5168
	s_waitcnt lgkmcnt(0)
	ds_read2_b32 v[66:67], v129 offset0:0 offset1:20
	ds_read2_b32 v[68:69], v129 offset0:40 offset1:60
	ds_read2_b32 v[70:71], v129 offset0:80 offset1:100
	ds_read2_b32 v[72:73], v129 offset0:120 offset1:140
	v_add_u32_e32 v3, 0xa00, v129
	ds_read2_b32 v[102:103], v3 offset0:0 offset1:20
	ds_read2_b32 v[104:105], v3 offset0:40 offset1:60
	ds_read2_b32 v[106:107], v3 offset0:80 offset1:100
	ds_read2_b32 v[108:109], v3 offset0:120 offset1:140
	v_add_u32_e32 v3, 0x1400, v129
	ds_read2_b32 v[110:111], v3 offset0:0 offset1:20
	ds_read2_b32 v[112:113], v3 offset0:40 offset1:60
	ds_read2_b32 v[114:115], v3 offset0:80 offset1:100
	ds_read2_b32 v[116:117], v3 offset0:120 offset1:140
	v_add_u32_e32 v3, 0x1e00, v129
	ds_read2_b32 v[132:133], v3 offset0:0 offset1:20
	ds_read2_b32 v[134:135], v3 offset0:40 offset1:60
	ds_read2_b32 v[136:137], v3 offset0:80 offset1:100
	ds_read2_b32 v[138:139], v3 offset0:120 offset1:140
	s_waitcnt lgkmcnt(12)
	v_cvt_pk_bf16_f32 v66, v66, v67
	v_cvt_pk_bf16_f32 v67, v68, v69
	v_cvt_pk_bf16_f32 v68, v70, v71
	v_cvt_pk_bf16_f32 v69, v72, v73
	s_waitcnt lgkmcnt(8)
	v_cvt_pk_bf16_f32 v102, v102, v103
	v_cvt_pk_bf16_f32 v103, v104, v105
	v_cvt_pk_bf16_f32 v104, v106, v107
	v_cvt_pk_bf16_f32 v105, v108, v109
	v_mfma_f32_16x16x32_bf16 v[62:65], v[42:45], v[66:69], 0
	s_waitcnt lgkmcnt(4)
	v_cvt_pk_bf16_f32 v110, v110, v111
	v_cvt_pk_bf16_f32 v111, v112, v113
	v_cvt_pk_bf16_f32 v112, v114, v115
	v_cvt_pk_bf16_f32 v113, v116, v117
	v_mfma_f32_16x16x32_bf16 v[62:65], v[46:49], v[102:105], v[62:65]
	s_waitcnt lgkmcnt(0)
	v_cvt_pk_bf16_f32 v132, v132, v133
	v_cvt_pk_bf16_f32 v133, v134, v135
	v_cvt_pk_bf16_f32 v134, v136, v137
	v_cvt_pk_bf16_f32 v135, v138, v139
	v_mfma_f32_16x16x32_bf16 v[62:65], v[50:53], v[110:113], v[62:65]
	s_waitcnt vmcnt(0)
	v_lshlrev_b32_e32 v70, 16, v100
	v_and_b32_e32 v71, 0xffff0000, v100
	v_mfma_f32_16x16x32_bf16 v[62:65], v[54:57], v[132:135], v[62:65]
	v_lshlrev_b32_e32 v72, 16, v101
	v_and_b32_e32 v73, 0xffff0000, v101
	s_nop 7
	v_fmac_f32_e32 v62, v38, v70
	v_fmac_f32_e32 v63, v39, v71
	v_fmac_f32_e32 v64, v40, v72
	v_fmac_f32_e32 v65, v41, v73
	v_mul_f32_e32 v70, 0x3d372713, v62
	v_mul_f32_e32 v71, 0x3d372713, v63
	v_mul_f32_e32 v72, 0x3d372713, v64
	v_mul_f32_e32 v73, 0x3d372713, v65
	v_mul_f32_e32 v70, v62, v70
	v_mul_f32_e32 v71, v63, v71
	v_mul_f32_e32 v72, v64, v72
	v_mul_f32_e32 v73, v65, v73
	v_fma_f32 v70, v62, v70, v62
	v_fma_f32 v71, v63, v71, v63
	v_fma_f32 v72, v64, v72, v64
	v_fma_f32 v73, v65, v73, v65
	v_mul_f32_e32 v70, 0x3f4c422a, v70
	v_mul_f32_e32 v71, 0x3f4c422a, v71
	v_mul_f32_e32 v72, 0x3f4c422a, v72
	v_mul_f32_e32 v73, 0x3f4c422a, v73
	v_mul_f32_e32 v70, -2.0, v70
	v_mul_f32_e32 v71, -2.0, v71
	v_mul_f32_e32 v72, -2.0, v72
	v_mul_f32_e32 v73, -2.0, v73
	v_mul_f32_e32 v70, 0x3fb8aa3b, v70
	v_mul_f32_e32 v71, 0x3fb8aa3b, v71
	v_mul_f32_e32 v72, 0x3fb8aa3b, v72
	v_mul_f32_e32 v73, 0x3fb8aa3b, v73
	v_exp_f32_e32 v70, v70
	v_exp_f32_e32 v71, v71
	v_exp_f32_e32 v72, v72
	v_exp_f32_e32 v73, v73
	v_add_f32_e32 v70, 1.0, v70
	v_add_f32_e32 v71, 1.0, v71
	v_add_f32_e32 v72, 1.0, v72
	v_add_f32_e32 v73, 1.0, v73
	v_rcp_f32_e32 v70, v70
	v_rcp_f32_e32 v71, v71
	v_rcp_f32_e32 v72, v72
	v_rcp_f32_e32 v73, v73
	v_mul_f32_e32 v62, v62, v70
	v_mul_f32_e32 v63, v63, v71
	v_mul_f32_e32 v64, v64, v72
	v_mul_f32_e32 v65, v65, v73
	v_cvt_pk_bf16_f32 v62, v62, v63
	v_cvt_pk_bf16_f32 v63, v64, v65
	global_store_dwordx2 v[4:5], v[62:63], off
	s_branch .LBB0_363
.Ls5p_scan0:
	s_waitcnt lgkmcnt(6)
	v_fmac_f32_e32 v66, v80, v99
	v_fmac_f32_e32 v110, v80, v98
	v_fmac_f32_e32 v66, v74, v98
	v_fmac_f32_e32 v110, v78, v99
	v_fmac_f32_e32 v67, v80, v66
	v_fmac_f32_e32 v111, v80, v110
	v_fmac_f32_e32 v67, v74, v110
	v_fmac_f32_e32 v111, v78, v66
	v_fmac_f32_e32 v68, v80, v67
	v_fmac_f32_e32 v112, v80, v111
	v_fmac_f32_e32 v68, v74, v111
	v_fmac_f32_e32 v112, v78, v67
	v_fmac_f32_e32 v69, v80, v68
	v_fmac_f32_e32 v113, v80, v112
	v_fmac_f32_e32 v69, v74, v112
	v_fmac_f32_e32 v113, v78, v68
	s_waitcnt lgkmcnt(4)
	v_fmac_f32_e32 v70, v80, v69
	v_fmac_f32_e32 v114, v80, v113
	v_fmac_f32_e32 v70, v74, v113
	v_fmac_f32_e32 v114, v78, v69
	v_fmac_f32_e32 v71, v80, v70
	v_fmac_f32_e32 v115, v80, v114
	v_fmac_f32_e32 v71, v74, v114
	v_fmac_f32_e32 v115, v78, v70
	v_fmac_f32_e32 v72, v80, v71
	v_fmac_f32_e32 v116, v80, v115
	v_fmac_f32_e32 v72, v74, v115
	v_fmac_f32_e32 v116, v78, v71
	v_fmac_f32_e32 v73, v80, v72
	v_fmac_f32_e32 v117, v80, v116
	v_fmac_f32_e32 v73, v74, v116
	v_fmac_f32_e32 v117, v78, v72
	s_waitcnt lgkmcnt(2)
	v_fmac_f32_e32 v102, v80, v73
	v_fmac_f32_e32 v132, v80, v117
	v_fmac_f32_e32 v102, v74, v117
	v_fmac_f32_e32 v132, v78, v73
	v_fmac_f32_e32 v103, v80, v102
	v_fmac_f32_e32 v133, v80, v132
	v_fmac_f32_e32 v103, v74, v132
	v_fmac_f32_e32 v133, v78, v102
	v_fmac_f32_e32 v104, v80, v103
	v_fmac_f32_e32 v134, v80, v133
	v_fmac_f32_e32 v104, v74, v133
	v_fmac_f32_e32 v134, v78, v103
	v_fmac_f32_e32 v105, v80, v104
	v_fmac_f32_e32 v135, v80, v134
	v_fmac_f32_e32 v105, v74, v134
	v_fmac_f32_e32 v135, v78, v104
	s_waitcnt lgkmcnt(0)
	v_fmac_f32_e32 v106, v80, v105
	v_fmac_f32_e32 v136, v80, v135
	v_fmac_f32_e32 v106, v74, v135
	v_fmac_f32_e32 v136, v78, v105
	v_fmac_f32_e32 v107, v80, v106
	v_fmac_f32_e32 v137, v80, v136
	v_fmac_f32_e32 v107, v74, v136
	v_fmac_f32_e32 v137, v78, v106
	v_fmac_f32_e32 v108, v80, v107
	v_fmac_f32_e32 v138, v80, v137
	v_fmac_f32_e32 v108, v74, v137
	v_fmac_f32_e32 v138, v78, v107
	v_fmac_f32_e32 v109, v80, v108
	v_fmac_f32_e32 v139, v80, v138
	v_fmac_f32_e32 v109, v74, v138
	v_fmac_f32_e32 v139, v78, v108
	v_mov_b32_e32 v99, v109
	v_mov_b32_e32 v98, v139
.LBB0_363:
	s_add_u32 s24, s24, 0x24000
	s_addc_u32 s25, s25, 0
	s_cmp_lg_u32 s24, 0x240000
	s_cbranch_scc0 .LBB0_346
	s_waitcnt vmcnt(0)
	v_mov_b64_e32 v[64:65], v[60:61]
	v_mov_b64_e32 v[62:63], v[58:59]
	s_branch .LBB0_357
